# MLA dense loop: K1/V tile loads use SGPR-base addressing with per-unit bases (drops two 64-bit VALU add chains and three s_nop per tile)
# baseline (speedup 1.0000x reference)
; #define AC_LOAD(kt_) do { kreg = *(const u32x4*)(kp1 + (size_t)(64 * (kt_)) * u.k1pitch); vreg = *(const u32x4*)(vp1 + (size_t)(64 * (kt_)) * u.vpitch); \
;         if (tid < 256) k2reg = *(const u32x4*)(kp2 + (size_t)(64 * (kt_)) * u.k2pitch); } while (0)
; #define AC_STORE(kt_) do { LAS unsigned char* Kb_ = lds + ((kt_) & 1) * AC_KBUF; LAS unsigned char* Vb_ = lds + AC_VOFF + ((kt_) % 3) * AC_VBUF; \
;         *(LAS u32x4*)(Kb_ + skey * AC_KP + 16 * sch) = kreg; *(LAS u32x4*)(Vb_ + skey * AC_VP + 16 * sch) = vreg; \
;         if (tid < 256) *(LAS u32x4*)(Kb_ + skey2 * AC_KP + 128 + 16 * sch2) = k2reg; } while (0)
; __device__ __forceinline__ void attn_unit_c(LAS unsigned char* lds, const AU& u, int tid, int wid, int lane) {
;     ...
;     for (int t = 0; t < NT; t += 2) {
;         AC_STORE(t + 1);
;         __syncthreads();
;         if (t + 2 < NT) AC_LOAD(t + 2);
;         AC_QK(pB0, pB1, t + 1);
;         AC_SOFTMAX_PV(pA0, pA1, pB0, pB1, t);
;         if (t + 2 < NT) AC_STORE(t + 2);
;         __syncthreads();
;         if (t + 3 < NT) AC_LOAD(t + 3);
.LBB0_839:
	s_lshr_b32 s1, s74, 4
	s_and_b32 s1, s1, 3
	s_lshl_b32 s1, s1, 12
	s_add_i32 s0, s0, s1
	s_mov_b32 s1, s31
	s_lshl_b64 s[0:1], s[0:1], 7
	v_ashrrev_i32_e32 v153, 31, v152
	v_lshl_add_u64 v[114:115], v[180:181], 0, s[0:1]
	s_add_u32 s98, s14, 0x3c08000
	s_addc_u32 s99, s15, 0
	s_add_u32 s100, s14, 0x4c08000
	s_addc_u32 s101, s15, 0
	v_lshl_add_u64 v[154:155], v[176:177], 0, s[6:7]
	s_mov_b32 s1, 2
.LBB0_840:
	s_or_b32 s0, s1, 1
	s_and_b32 s4, s0, 0xff
	s_mulk_i32 s4, 0xab
	s_bfe_u32 s4, s4, 0x70009
	s_mul_i32 s4, s4, 3
	s_sub_i32 s0, s0, s4
	s_and_b32 s0, s0, 0xff
	s_mulk_i32 s0, 0x3000
	s_add_i32 s0, s0, 0
	v_add3_u32 v33, s0, v203, v174
	s_waitcnt vmcnt(1)
	ds_write_b128 v112, v[144:147] offset:13312
	s_waitcnt vmcnt(0)
	ds_write_b128 v33, v[148:151] offset:26624
	s_and_saveexec_b64 s[4:5], s[10:11]
	ds_write_b128 v210, v[140:143] offset:13440
	s_or_b64 exec, exec, s[4:5]
	s_cmp_lt_u32 s1, 62
	s_cselect_b64 s[18:19], -1, 0
	s_cmp_gt_u32 s1, 61
	s_cselect_b64 s[6:7], -1, 0
	s_and_b64 vcc, exec, s[6:7]
	s_waitcnt lgkmcnt(0)
	s_barrier
	s_cbranch_vccnz .LBB0_846
	global_load_dwordx4 v[144:147], v114, s[98:99]
	global_load_dwordx4 v[148:151], v114, s[100:101]
	s_and_saveexec_b64 s[4:5], s[10:11]
	s_cbranch_execz .LBB0_845
	v_lshl_add_u64 v[34:35], s[14:15], 0, v[154:155]
	v_add_co_u32_e32 v34, vcc, 0x1d404000, v34
	s_nop 1
	v_addc_co_u32_e32 v35, vcc, 0, v35, vcc
	global_load_dwordx4 v[140:143], v[34:35], off

; #define AC_LOAD(kt_) do { kreg = *(const u32x4*)(kp1 + (size_t)(64 * (kt_)) * u.k1pitch); vreg = *(const u32x4*)(vp1 + (size_t)(64 * (kt_)) * u.vpitch); \
;         if (tid < 256) k2reg = *(const u32x4*)(kp2 + (size_t)(64 * (kt_)) * u.k2pitch); } while (0)
; #define AC_STORE(kt_) do { LAS unsigned char* Kb_ = lds + ((kt_) & 1) * AC_KBUF; LAS unsigned char* Vb_ = lds + AC_VOFF + ((kt_) % 3) * AC_VBUF; \
;         *(LAS u32x4*)(Kb_ + skey * AC_KP + 16 * sch) = kreg; *(LAS u32x4*)(Vb_ + skey * AC_VP + 16 * sch) = vreg; \
;         if (tid < 256) *(LAS u32x4*)(Kb_ + skey2 * AC_KP + 128 + 16 * sch2) = k2reg; } while (0)
; __device__ __forceinline__ void attn_unit_c(LAS unsigned char* lds, const AU& u, int tid, int wid, int lane) {
;     ...
;         if (t + 2 < NT) AC_LOAD(t + 2);
;         AC_QK(pB0, pB1, t + 1);
;         AC_SOFTMAX_PV(pA0, pA1, pB0, pB1, t);
;         if (t + 2 < NT) AC_STORE(t + 2);
;         __syncthreads();
;         if (t + 3 < NT) AC_LOAD(t + 3);
.LBB0_852:
	s_cmp_gt_u32 s1, 60
	s_waitcnt lgkmcnt(0)
	s_barrier
	s_cbranch_scc1 .LBB0_856
	v_add_u32_e32 v42, 0x2000, v114
	global_load_dwordx4 v[144:147], v42, s[98:99]
	global_load_dwordx4 v[148:151], v42, s[100:101]
	s_and_saveexec_b64 s[4:5], s[10:11]
	s_cbranch_execz .LBB0_855
	v_lshl_add_u64 v[42:43], s[14:15], 0, v[154:155]
	v_add_co_u32_e32 v42, vcc, 0x1d405000, v42
	s_nop 1
	v_addc_co_u32_e32 v43, vcc, 0, v43, vcc
	global_load_dwordx4 v[140:143], v[42:43], off
